# diff-attention side job: LDS reads of the landed item issued before the item decode
# speedup vs baseline: 1.0004x; 1.0004x over previous
; __device__ __forceinline__ void side_drain(const SideJob& J, int i, int tid, char* lds) {
;   const SideItem t = side_item(J, i);
;   const int n = tid >> 3, kc = tid & 7;
;   const float* R = (const float*)(lds + LDS_SJ_R + (i & 1) * 16384) + (8 * kc) * 64 + 4 * ((n >> 2) ^ kc) + (n & 3);
;   float v[8];
; #pragma unroll
;   for (int j = 0; j < 8; ++j) v[j] = R[j * 64];
.LBB0_421:
	s_andn2_b64 vcc, exec, s[28:29]
	s_cbranch_vccnz .LBB0_432
	s_lshl_b32 s98, s88, 14
	s_and_b32 s98, s98, 0x4000
	v_add_u32_e32 v86, s98, v198
	ds_read2st64_b32 v[92:93], v86 offset1:1
	ds_read2st64_b32 v[90:91], v86 offset0:2 offset1:3
	ds_read2st64_b32 v[88:89], v86 offset0:4 offset1:5
	ds_read2st64_b32 v[86:87], v86 offset0:6 offset1:7
	s_lshl_b32 s53, s88, 8
	s_add_i32 s53, s53, s76
	s_cmpk_gt_i32 s53, 0x3ff
	s_mov_b64 s[38:39], -1
	s_cbranch_scc0 .LBB0_427
	s_lshl_b32 s73, s53, 6
	s_cmpk_gt_u32 s53, 0x13ff
	s_mov_b64 s[28:29], -1
	s_cbranch_scc0 .LBB0_425
	s_lshl_b32 s28, s53, 1
	s_add_i32 s28, s28, 0x7fffd800
	s_and_b32 s40, s28, 0x7fffffc0
	s_and_b32 s41, s73, 0x7c0
	s_mov_b64 s[28:29], 0

; __device__ __forceinline__ void side_drain(const SideJob& J, int i, int tid, char* lds) {
;   const SideItem t = side_item(J, i);
;   const int n = tid >> 3, kc = tid & 7;
;   const float* R = (const float*)(lds + LDS_SJ_R + (i & 1) * 16384) + (8 * kc) * 64 + 4 * ((n >> 2) ^ kc) + (n & 3);
;   float v[8];
; #pragma unroll
;   for (int j = 0; j < 8; ++j) v[j] = R[j * 64];
;   if (t.gain) { const float* gl = (const float*)(lds + LDS_SJ_G) + t.k0 + 8 * kc;
; #pragma unroll
;     for (int j = 0; j < 8; ++j) v[j] *= gl[j]; }
.LBB0_429:
	s_lshl_b32 s38, s88, 14
	s_and_b32 s38, s38, 0x4000
	s_andn2_b64 vcc, exec, s[36:37]
	s_cbranch_vccnz .LBB0_431
	v_lshl_add_u32 v100, s40, 2, v200
	ds_read_b128 v[94:97], v100
	ds_read_b128 v[100:103], v100 offset:16
	s_waitcnt lgkmcnt(1)
	v_pk_mul_f32 v[92:93], v[92:93], v[94:95]
	v_pk_mul_f32 v[90:91], v[90:91], v[96:97]
	s_waitcnt lgkmcnt(0)
	v_pk_mul_f32 v[88:89], v[88:89], v[100:101]
	v_pk_mul_f32 v[86:87], v[86:87], v[102:103]
